# in-projection GEMM loop: inverted priorities (load segment at prio 1, MFMA segment at prio 0)
# baseline (speedup 1.0000x reference)
; #define PG8_STAGE(bufoff, gbase, voff) do { _Pragma("unroll") for (int _i = 0; _i < 2; ++_i) \
;         __builtin_amdgcn_global_load_lds((const unsigned*)((const char*)(gbase) + (voff)[_i]), (LAS unsigned*)(lds + (bufoff) + ldsw + _i * 8192), 16, 0, 0); } while (0)
; #define PG8_LDA(dst, b, h) do { _Pragma("unroll") for (int m = 0; m < 4; ++m) _Pragma("unroll") for (int k = 0; k < 2; ++k) dst[m][k] = *(const LAS bf16x8*)(lds + PG8_SA(b, h) + aoff + m * 2048 + k * 1024); } while (0)
; #define PG8_LDB(dst, b, h) do { _Pragma("unroll") for (int n = 0; n < 2; ++n) _Pragma("unroll") for (int k = 0; k < 2; ++k) dst[n][k] = *(const LAS bf16x8*)(lds + PG8_SB(b, h) + boff + n * 2048 + k * 1024); } while (0)
; #define PG8_MMA(ai, bj, At, Bt) do { __builtin_amdgcn_s_setprio(1); _Pragma("unroll") for (int m = 0; m < 4; ++m) _Pragma("unroll") for (int n = 0; n < 2; ++n) _Pragma("unroll") for (int k = 0; k < 2; ++k) \
;         acc[ai][bj][m][n] = __builtin_amdgcn_mfma_f32_16x16x32_bf16(Bt[n][k], At[m][k], acc[ai][bj][m][n], 0, 0, 0); __builtin_amdgcn_s_setprio(0); } while (0)
; #define PG8_WAIT_V(n) asm volatile("s_waitcnt vmcnt(" #n ")" ::: "memory")
; #define PG8_WAIT_L(n) asm volatile("s_waitcnt lgkmcnt(" #n ")" ::: "memory")
; #define PG8_BAR __builtin_amdgcn_s_barrier()
; #define PG8_SCHED __builtin_amdgcn_sched_barrier(0)
; template <class Epi, class Sched>
; __device__ __forceinline__ void gemm_phase(LAS unsigned char* lds, const Gemm g, const Sched& S, const Epi& E, const int tid) {
;     ...
;             PG8_LDB(B0, 0, 0); PG8_LDB(B1, 0, 1); PG8_SCHED; PG8_LDA(At, 0, 0); PG8_STAGE(PG8_SA(1, 1), a1 + hstepA, voffA);
;             PG8_WAIT_V(8); PG8_WAIT_L(0); PG8_BAR; PG8_MMA(0, 0, At, B0); PG8_MMA(0, 1, At, B1); PG8_BAR; PG8_SCHED;
;             PG8_LDA(At, 0, 1); PG8_STAGE(PG8_SB(0, 0), b2, voffB); PG8_STAGE(PG8_SB(0, 1), b2 + hstepB, voffB); PG8_STAGE(PG8_SA(0, 0), a2, voffA);
.LBB0_347:
	s_add_u32 s24, s2, 0xfff80080
	s_addc_u32 s26, s3, -1
	s_add_i32 s31, 0, 0x10000
	s_cmp_eq_u32 s22, 28
	s_cselect_b32 s49, s15, s26
	s_cselect_b32 s48, s16, s24
	s_cselect_b32 s39, s11, s21
	s_cselect_b32 s38, s19, s20
	s_add_i32 s24, 0, 0x14000
	v_add_u32_e32 v140, s31, v158
	v_add_u32_e32 v154, s24, v158
	ds_read_b128 v[128:131], v140
	ds_read_b128 v[132:135], v140 offset:1024
	ds_read_b128 v[136:139], v140 offset:2048
	ds_read_b128 v[140:143], v140 offset:3072
	ds_read_b128 v[160:163], v154
	ds_read_b128 v[164:167], v154 offset:1024
	ds_read_b128 v[168:171], v154 offset:2048
	ds_read_b128 v[172:175], v154 offset:3072
	v_lshl_add_u64 v[154:155], s[2:3], 0, v[150:151]
	s_add_i32 m0, s45, 0xc000
	ds_read_b128 v[176:179], v159
	ds_read_b128 v[180:183], v159 offset:1024
	ds_read_b128 v[184:187], v159 offset:2048
	ds_read_b128 v[188:191], v159 offset:3072
	ds_read_b128 v[202:205], v159 offset:4096
	ds_read_b128 v[206:209], v159 offset:5120
	ds_read_b128 v[210:213], v159 offset:6144
	ds_read_b128 v[214:217], v159 offset:7168
	global_load_lds_dwordx4 v[154:155], off
	v_lshl_add_u64 v[154:155], s[2:3], 0, v[152:153]
	s_add_i32 m0, s45, 0xe000
	s_nop 0
	global_load_lds_dwordx4 v[154:155], off
	s_waitcnt vmcnt(8)
	s_waitcnt lgkmcnt(0)
	s_barrier
	s_setprio 0
	s_waitcnt lgkmcnt(0)
	v_mfma_f32_16x16x32_bf16 v[124:127], v[128:131], v[176:179], v[124:127]
	v_mfma_f32_16x16x32_bf16 v[120:123], v[136:139], v[176:179], v[120:123]
	v_mfma_f32_16x16x32_bf16 v[108:111], v[128:131], v[184:187], v[108:111]
	v_mfma_f32_16x16x32_bf16 v[104:107], v[136:139], v[184:187], v[104:107]
	v_mfma_f32_16x16x32_bf16 v[92:95], v[128:131], v[202:205], v[92:95]
	v_mfma_f32_16x16x32_bf16 v[88:91], v[136:139], v[202:205], v[88:91]
	v_mfma_f32_16x16x32_bf16 v[76:79], v[128:131], v[210:213], v[76:79]
	v_mfma_f32_16x16x32_bf16 v[72:75], v[136:139], v[210:213], v[72:75]
	v_mfma_f32_16x16x32_bf16 v[124:127], v[132:135], v[180:183], v[124:127]
	v_mfma_f32_16x16x32_bf16 v[120:123], v[140:143], v[180:183], v[120:123]
	v_mfma_f32_16x16x32_bf16 v[108:111], v[132:135], v[188:191], v[108:111]
	v_mfma_f32_16x16x32_bf16 v[104:107], v[140:143], v[188:191], v[104:107]
	v_mfma_f32_16x16x32_bf16 v[92:95], v[132:135], v[206:209], v[92:95]
	v_mfma_f32_16x16x32_bf16 v[88:91], v[140:143], v[206:209], v[88:91]
	v_mfma_f32_16x16x32_bf16 v[76:79], v[132:135], v[214:217], v[76:79]
	v_mfma_f32_16x16x32_bf16 v[72:75], v[140:143], v[214:217], v[72:75]
	v_mfma_f32_16x16x32_bf16 v[116:119], v[160:163], v[176:179], v[116:119]
	v_mfma_f32_16x16x32_bf16 v[112:115], v[168:171], v[176:179], v[112:115]
	v_mfma_f32_16x16x32_bf16 v[100:103], v[160:163], v[184:187], v[100:103]
	v_mfma_f32_16x16x32_bf16 v[96:99], v[168:171], v[184:187], v[96:99]
	v_mfma_f32_16x16x32_bf16 v[84:87], v[160:163], v[202:205], v[84:87]
	v_mfma_f32_16x16x32_bf16 v[80:83], v[168:171], v[202:205], v[80:83]
	v_mfma_f32_16x16x32_bf16 v[68:71], v[160:163], v[210:213], v[68:71]
	v_mfma_f32_16x16x32_bf16 v[64:67], v[168:171], v[210:213], v[64:67]
	v_mfma_f32_16x16x32_bf16 v[116:119], v[164:167], v[180:183], v[116:119]
	v_mfma_f32_16x16x32_bf16 v[112:115], v[172:175], v[180:183], v[112:115]
	v_mfma_f32_16x16x32_bf16 v[100:103], v[164:167], v[188:191], v[100:103]
	v_mfma_f32_16x16x32_bf16 v[96:99], v[172:175], v[188:191], v[96:99]
	v_mfma_f32_16x16x32_bf16 v[84:87], v[164:167], v[206:209], v[84:87]
	v_mfma_f32_16x16x32_bf16 v[80:83], v[172:175], v[206:209], v[80:83]
	v_mfma_f32_16x16x32_bf16 v[68:71], v[164:167], v[214:217], v[68:71]
	v_mfma_f32_16x16x32_bf16 v[64:67], v[172:175], v[214:217], v[64:67]
	s_setprio 1
	s_barrier
	s_add_i32 s26, s31, s25
	v_lshl_add_u64 v[154:155], s[38:39], 0, v[192:193]
	s_mov_b32 m0, s26
	ds_read_b128 v[176:179], v159 offset:16384
	ds_read_b128 v[180:183], v159 offset:17408
	ds_read_b128 v[184:187], v159 offset:18432
	ds_read_b128 v[188:191], v159 offset:19456
	ds_read_b128 v[202:205], v159 offset:20480
	ds_read_b128 v[206:209], v159 offset:21504
	ds_read_b128 v[210:213], v159 offset:22528
	ds_read_b128 v[214:217], v159 offset:23552
	global_load_lds_dwordx4 v[154:155], off
	s_add_i32 m0, s26, 0x2000
	s_add_u32 s64, s38, 0x80000
	v_lshl_add_u64 v[218:219], s[38:39], 0, v[148:149]
	s_addc_u32 s65, s39, 0
	s_add_i32 s24, s24, s25
	global_load_lds_dwordx4 v[218:219], off
	v_lshl_add_u64 v[220:221], s[64:65], 0, v[192:193]
	s_mov_b32 m0, s24
	v_lshl_add_u64 v[222:223], s[48:49], 0, v[146:147]
	global_load_lds_dwordx4 v[220:221], off
	v_lshl_add_u64 v[220:221], s[64:65], 0, v[148:149]
	s_add_i32 m0, s24, 0x2000
	s_nop 0
	global_load_lds_dwordx4 v[220:221], off
	v_lshl_add_u64 v[220:221], s[48:49], 0, v[144:145]
	s_mov_b32 m0, s45
	s_nop 0
	global_load_lds_dwordx4 v[220:221], off
	s_mov_b32 m0, s47
	s_nop 0
	global_load_lds_dwordx4 v[222:223], off
	s_waitcnt vmcnt(8)
	s_waitcnt lgkmcnt(0)
	s_barrier
; #define PG8_STAGE(bufoff, gbase, voff) do { _Pragma("unroll") for (int _i = 0; _i < 2; ++_i) \
;         __builtin_amdgcn_global_load_lds((const unsigned*)((const char*)(gbase) + (voff)[_i]), (LAS unsigned*)(lds + (bufoff) + ldsw + _i * 8192), 16, 0, 0); } while (0)
; #define PG8_LDA(dst, b, h) do { _Pragma("unroll") for (int m = 0; m < 4; ++m) _Pragma("unroll") for (int k = 0; k < 2; ++k) dst[m][k] = *(const LAS bf16x8*)(lds + PG8_SA(b, h) + aoff + m * 2048 + k * 1024); } while (0)
; #define PG8_LDB(dst, b, h) do { _Pragma("unroll") for (int n = 0; n < 2; ++n) _Pragma("unroll") for (int k = 0; k < 2; ++k) dst[n][k] = *(const LAS bf16x8*)(lds + PG8_SB(b, h) + boff + n * 2048 + k * 1024); } while (0)
; #define PG8_MMA(ai, bj, At, Bt) do { __builtin_amdgcn_s_setprio(1); _Pragma("unroll") for (int m = 0; m < 4; ++m) _Pragma("unroll") for (int n = 0; n < 2; ++n) _Pragma("unroll") for (int k = 0; k < 2; ++k) \
;         acc[ai][bj][m][n] = __builtin_amdgcn_mfma_f32_16x16x32_bf16(Bt[n][k], At[m][k], acc[ai][bj][m][n], 0, 0, 0); __builtin_amdgcn_s_setprio(0); } while (0)
; #define PG8_WAIT_V(n) asm volatile("s_waitcnt vmcnt(" #n ")" ::: "memory")
; #define PG8_WAIT_L(n) asm volatile("s_waitcnt lgkmcnt(" #n ")" ::: "memory")
; #define PG8_BAR __builtin_amdgcn_s_barrier()
; #define PG8_SCHED __builtin_amdgcn_sched_barrier(0)
; template <class Epi, class Sched>
; __device__ __forceinline__ void gemm_phase(LAS unsigned char* lds, const Gemm g, const Sched& S, const Epi& E, const int tid) {
;     ...
;             PG8_WAIT_V(8); PG8_WAIT_L(0); PG8_BAR; PG8_MMA(1, 0, At, B0); PG8_MMA(1, 1, At, B1); PG8_BAR; PG8_SCHED;
;             PG8_LDB(B0, 1, 0); PG8_LDB(B1, 1, 1); PG8_SCHED; PG8_LDA(At, 1, 0); PG8_STAGE(PG8_SA(0, 1), a2 + hstepA, voffA);
;             PG8_WAIT_V(8); PG8_WAIT_L(0); PG8_BAR; PG8_MMA(0, 0, At, B0); PG8_MMA(0, 1, At, B1); PG8_BAR; PG8_SCHED;
	s_setprio 0
	s_waitcnt lgkmcnt(0)
	v_mfma_f32_16x16x32_bf16 v[60:63], v[128:131], v[176:179], v[60:63]
	v_mfma_f32_16x16x32_bf16 v[56:59], v[136:139], v[176:179], v[56:59]
	v_mfma_f32_16x16x32_bf16 v[44:47], v[128:131], v[184:187], v[44:47]
	v_mfma_f32_16x16x32_bf16 v[40:43], v[136:139], v[184:187], v[40:43]
	v_mfma_f32_16x16x32_bf16 v[28:31], v[128:131], v[202:205], v[28:31]
	v_mfma_f32_16x16x32_bf16 v[24:27], v[136:139], v[202:205], v[24:27]
	v_mfma_f32_16x16x32_bf16 v[12:15], v[128:131], v[210:213], v[12:15]
	v_mfma_f32_16x16x32_bf16 v[8:11], v[136:139], v[210:213], v[8:11]
	v_mfma_f32_16x16x32_bf16 v[60:63], v[132:135], v[180:183], v[60:63]
	v_mfma_f32_16x16x32_bf16 v[56:59], v[140:143], v[180:183], v[56:59]
	v_mfma_f32_16x16x32_bf16 v[44:47], v[132:135], v[188:191], v[44:47]
	v_mfma_f32_16x16x32_bf16 v[40:43], v[140:143], v[188:191], v[40:43]
	v_mfma_f32_16x16x32_bf16 v[28:31], v[132:135], v[206:209], v[28:31]
	v_mfma_f32_16x16x32_bf16 v[24:27], v[140:143], v[206:209], v[24:27]
	v_mfma_f32_16x16x32_bf16 v[12:15], v[132:135], v[214:217], v[12:15]
	v_mfma_f32_16x16x32_bf16 v[8:11], v[140:143], v[214:217], v[8:11]
	v_mfma_f32_16x16x32_bf16 v[52:55], v[160:163], v[176:179], v[52:55]
	v_mfma_f32_16x16x32_bf16 v[48:51], v[168:171], v[176:179], v[48:51]
	v_mfma_f32_16x16x32_bf16 v[36:39], v[160:163], v[184:187], v[36:39]
	v_mfma_f32_16x16x32_bf16 v[32:35], v[168:171], v[184:187], v[32:35]
	v_mfma_f32_16x16x32_bf16 v[20:23], v[160:163], v[202:205], v[20:23]
	v_mfma_f32_16x16x32_bf16 v[16:19], v[168:171], v[202:205], v[16:19]
	v_mfma_f32_16x16x32_bf16 v[4:7], v[160:163], v[210:213], v[4:7]
	v_mfma_f32_16x16x32_bf16 v[0:3], v[168:171], v[210:213], v[0:3]
	v_mfma_f32_16x16x32_bf16 v[52:55], v[164:167], v[180:183], v[52:55]
	v_mfma_f32_16x16x32_bf16 v[48:51], v[172:175], v[180:183], v[48:51]
	v_mfma_f32_16x16x32_bf16 v[36:39], v[164:167], v[188:191], v[36:39]
	v_mfma_f32_16x16x32_bf16 v[32:35], v[172:175], v[188:191], v[32:35]
	v_mfma_f32_16x16x32_bf16 v[20:23], v[164:167], v[206:209], v[20:23]
	v_mfma_f32_16x16x32_bf16 v[16:19], v[172:175], v[206:209], v[16:19]
	v_mfma_f32_16x16x32_bf16 v[4:7], v[164:167], v[214:217], v[4:7]
	v_mfma_f32_16x16x32_bf16 v[0:3], v[172:175], v[214:217], v[0:3]
	s_setprio 1
	s_barrier
	s_add_i32 s24, 0, 0x18000
	s_add_i32 s26, 0, 0x1c000
	v_add_u32_e32 v140, s24, v158
	v_add_u32_e32 v172, s26, v158
	ds_read_b128 v[128:131], v140
	ds_read_b128 v[132:135], v140 offset:1024
	ds_read_b128 v[136:139], v140 offset:2048
	ds_read_b128 v[140:143], v140 offset:3072
	ds_read_b128 v[160:163], v172
	ds_read_b128 v[164:167], v172 offset:1024
	ds_read_b128 v[168:171], v172 offset:2048
	ds_read_b128 v[172:175], v172 offset:3072
	s_add_u32 s48, s48, 0x80000
	s_addc_u32 s49, s49, 0
	s_mov_b32 m0, s52
	v_lshl_add_u64 v[234:235], s[48:49], 0, v[144:145]
	ds_read_b128 v[176:179], v159 offset:32768
	ds_read_b128 v[180:183], v159 offset:33792
	ds_read_b128 v[184:187], v159 offset:34816
	ds_read_b128 v[188:191], v159 offset:35840
	ds_read_b128 v[202:205], v159 offset:36864
	ds_read_b128 v[206:209], v159 offset:37888
	ds_read_b128 v[210:213], v159 offset:38912
	ds_read_b128 v[214:217], v159 offset:39936
	global_load_lds_dwordx4 v[234:235], off
	v_lshl_add_u64 v[234:235], s[48:49], 0, v[146:147]
	s_mov_b32 m0, s53
	s_nop 0
	global_load_lds_dwordx4 v[234:235], off
	s_waitcnt vmcnt(8)
	s_waitcnt lgkmcnt(0)
	s_barrier
	s_setprio 0
	s_waitcnt lgkmcnt(0)
	v_mfma_f32_16x16x32_bf16 v[124:127], v[128:131], v[176:179], v[124:127]
	v_mfma_f32_16x16x32_bf16 v[120:123], v[136:139], v[176:179], v[120:123]
	v_mfma_f32_16x16x32_bf16 v[108:111], v[128:131], v[184:187], v[108:111]
	v_mfma_f32_16x16x32_bf16 v[104:107], v[136:139], v[184:187], v[104:107]
	v_mfma_f32_16x16x32_bf16 v[92:95], v[128:131], v[202:205], v[92:95]
	v_mfma_f32_16x16x32_bf16 v[88:91], v[136:139], v[202:205], v[88:91]
	v_mfma_f32_16x16x32_bf16 v[76:79], v[128:131], v[210:213], v[76:79]
	v_mfma_f32_16x16x32_bf16 v[72:75], v[136:139], v[210:213], v[72:75]
	v_mfma_f32_16x16x32_bf16 v[124:127], v[132:135], v[180:183], v[124:127]
	v_mfma_f32_16x16x32_bf16 v[120:123], v[140:143], v[180:183], v[120:123]
	v_mfma_f32_16x16x32_bf16 v[108:111], v[132:135], v[188:191], v[108:111]
	v_mfma_f32_16x16x32_bf16 v[104:107], v[140:143], v[188:191], v[104:107]
	v_mfma_f32_16x16x32_bf16 v[92:95], v[132:135], v[206:209], v[92:95]
	v_mfma_f32_16x16x32_bf16 v[88:91], v[140:143], v[206:209], v[88:91]
	v_mfma_f32_16x16x32_bf16 v[76:79], v[132:135], v[214:217], v[76:79]
	v_mfma_f32_16x16x32_bf16 v[72:75], v[140:143], v[214:217], v[72:75]
	v_mfma_f32_16x16x32_bf16 v[116:119], v[160:163], v[176:179], v[116:119]
	v_mfma_f32_16x16x32_bf16 v[112:115], v[168:171], v[176:179], v[112:115]
	v_mfma_f32_16x16x32_bf16 v[100:103], v[160:163], v[184:187], v[100:103]
	v_mfma_f32_16x16x32_bf16 v[96:99], v[168:171], v[184:187], v[96:99]
	v_mfma_f32_16x16x32_bf16 v[84:87], v[160:163], v[202:205], v[84:87]
	v_mfma_f32_16x16x32_bf16 v[80:83], v[168:171], v[202:205], v[80:83]
	v_mfma_f32_16x16x32_bf16 v[68:71], v[160:163], v[210:213], v[68:71]
	v_mfma_f32_16x16x32_bf16 v[64:67], v[168:171], v[210:213], v[64:67]
	v_mfma_f32_16x16x32_bf16 v[116:119], v[164:167], v[180:183], v[116:119]
	v_mfma_f32_16x16x32_bf16 v[112:115], v[172:175], v[180:183], v[112:115]
	v_mfma_f32_16x16x32_bf16 v[100:103], v[164:167], v[188:191], v[100:103]
	v_mfma_f32_16x16x32_bf16 v[96:99], v[172:175], v[188:191], v[96:99]
	v_mfma_f32_16x16x32_bf16 v[84:87], v[164:167], v[206:209], v[84:87]
	v_mfma_f32_16x16x32_bf16 v[80:83], v[172:175], v[206:209], v[80:83]
	v_mfma_f32_16x16x32_bf16 v[68:71], v[164:167], v[214:217], v[68:71]
	v_mfma_f32_16x16x32_bf16 v[64:67], v[172:175], v[214:217], v[64:67]
	s_setprio 1
	s_barrier
; #define PG8_STAGE(bufoff, gbase, voff) do { _Pragma("unroll") for (int _i = 0; _i < 2; ++_i) \
;         __builtin_amdgcn_global_load_lds((const unsigned*)((const char*)(gbase) + (voff)[_i]), (LAS unsigned*)(lds + (bufoff) + ldsw + _i * 8192), 16, 0, 0); } while (0)
; #define PG8_LDA(dst, b, h) do { _Pragma("unroll") for (int m = 0; m < 4; ++m) _Pragma("unroll") for (int k = 0; k < 2; ++k) dst[m][k] = *(const LAS bf16x8*)(lds + PG8_SA(b, h) + aoff + m * 2048 + k * 1024); } while (0)
; #define PG8_MMA(ai, bj, At, Bt) do { __builtin_amdgcn_s_setprio(1); _Pragma("unroll") for (int m = 0; m < 4; ++m) _Pragma("unroll") for (int n = 0; n < 2; ++n) _Pragma("unroll") for (int k = 0; k < 2; ++k) \
;         acc[ai][bj][m][n] = __builtin_amdgcn_mfma_f32_16x16x32_bf16(Bt[n][k], At[m][k], acc[ai][bj][m][n], 0, 0, 0); __builtin_amdgcn_s_setprio(0); } while (0)
; #define PG8_WAIT_V(n) asm volatile("s_waitcnt vmcnt(" #n ")" ::: "memory")
; #define PG8_WAIT_L(n) asm volatile("s_waitcnt lgkmcnt(" #n ")" ::: "memory")
; #define PG8_BAR __builtin_amdgcn_s_barrier()
; #define PG8_SCHED __builtin_amdgcn_sched_barrier(0)
; template <class Epi, class Sched>
; __device__ __forceinline__ void gemm_phase(LAS unsigned char* lds, const Gemm g, const Sched& S, const Epi& E, const int tid) {
;     ...
;             PG8_LDA(At, 1, 1); PG8_STAGE(PG8_SB(1, 0), b3, voffB); PG8_STAGE(PG8_SB(1, 1), b3 + hstepB, voffB); PG8_STAGE(PG8_SA(1, 0), a3, voffA);
;             PG8_WAIT_V(8); PG8_WAIT_L(0); PG8_BAR; PG8_MMA(1, 0, At, B0); PG8_MMA(1, 1, At, B1); PG8_BAR; PG8_SCHED;
;         }
	s_add_i32 s24, s24, s25
	v_lshl_add_u64 v[154:155], v[154:155], 0, s[34:35]
	s_mov_b32 m0, s24
	ds_read_b128 v[176:179], v159 offset:49152
	ds_read_b128 v[180:183], v159 offset:50176
	ds_read_b128 v[184:187], v159 offset:51200
	ds_read_b128 v[188:191], v159 offset:52224
	ds_read_b128 v[202:205], v159 offset:53248
	ds_read_b128 v[206:209], v159 offset:54272
	ds_read_b128 v[210:213], v159 offset:55296
	ds_read_b128 v[214:217], v159 offset:56320
	global_load_lds_dwordx4 v[154:155], off
	s_add_i32 m0, s24, 0x2000
	s_add_u32 s38, s38, 0x80080
	v_lshl_add_u64 v[154:155], v[218:219], 0, s[34:35]
	s_addc_u32 s39, s39, 0
	s_add_i32 s24, s26, s25
	global_load_lds_dwordx4 v[154:155], off
	v_lshl_add_u64 v[154:155], s[38:39], 0, v[192:193]
	s_mov_b32 m0, s24
	s_nop 0
	global_load_lds_dwordx4 v[154:155], off
	v_lshl_add_u64 v[154:155], s[38:39], 0, v[148:149]
	s_add_i32 m0, s24, 0x2000
	s_nop 0
	global_load_lds_dwordx4 v[154:155], off
	v_lshl_add_u64 v[154:155], v[220:221], 0, s[34:35]
	s_mov_b32 m0, s56
	s_nop 0
	global_load_lds_dwordx4 v[154:155], off
	v_lshl_add_u64 v[154:155], v[222:223], 0, s[34:35]
	s_mov_b32 m0, s57
	s_nop 0
	global_load_lds_dwordx4 v[154:155], off
	s_waitcnt vmcnt(8)
	s_waitcnt lgkmcnt(0)
	s_barrier
	s_setprio 0
	s_waitcnt lgkmcnt(0)
	v_mfma_f32_16x16x32_bf16 v[60:63], v[128:131], v[176:179], v[60:63]
	v_mfma_f32_16x16x32_bf16 v[56:59], v[136:139], v[176:179], v[56:59]
	v_mfma_f32_16x16x32_bf16 v[44:47], v[128:131], v[184:187], v[44:47]
	v_mfma_f32_16x16x32_bf16 v[40:43], v[136:139], v[184:187], v[40:43]
	v_mfma_f32_16x16x32_bf16 v[28:31], v[128:131], v[202:205], v[28:31]
	v_mfma_f32_16x16x32_bf16 v[24:27], v[136:139], v[202:205], v[24:27]
	v_mfma_f32_16x16x32_bf16 v[12:15], v[128:131], v[210:213], v[12:15]
	v_mfma_f32_16x16x32_bf16 v[8:11], v[136:139], v[210:213], v[8:11]
	v_mfma_f32_16x16x32_bf16 v[60:63], v[132:135], v[180:183], v[60:63]
	v_mfma_f32_16x16x32_bf16 v[56:59], v[140:143], v[180:183], v[56:59]
	v_mfma_f32_16x16x32_bf16 v[44:47], v[132:135], v[188:191], v[44:47]
	v_mfma_f32_16x16x32_bf16 v[40:43], v[140:143], v[188:191], v[40:43]
	v_mfma_f32_16x16x32_bf16 v[28:31], v[132:135], v[206:209], v[28:31]
	v_mfma_f32_16x16x32_bf16 v[24:27], v[140:143], v[206:209], v[24:27]
	v_mfma_f32_16x16x32_bf16 v[12:15], v[132:135], v[214:217], v[12:15]
	v_mfma_f32_16x16x32_bf16 v[8:11], v[140:143], v[214:217], v[8:11]
	v_mfma_f32_16x16x32_bf16 v[52:55], v[160:163], v[176:179], v[52:55]
	v_mfma_f32_16x16x32_bf16 v[48:51], v[168:171], v[176:179], v[48:51]
	v_mfma_f32_16x16x32_bf16 v[36:39], v[160:163], v[184:187], v[36:39]
	v_mfma_f32_16x16x32_bf16 v[32:35], v[168:171], v[184:187], v[32:35]
	v_mfma_f32_16x16x32_bf16 v[20:23], v[160:163], v[202:205], v[20:23]
	v_mfma_f32_16x16x32_bf16 v[16:19], v[168:171], v[202:205], v[16:19]
	v_mfma_f32_16x16x32_bf16 v[4:7], v[160:163], v[210:213], v[4:7]
	v_mfma_f32_16x16x32_bf16 v[0:3], v[168:171], v[210:213], v[0:3]
	v_mfma_f32_16x16x32_bf16 v[52:55], v[164:167], v[180:183], v[52:55]
	v_mfma_f32_16x16x32_bf16 v[48:51], v[172:175], v[180:183], v[48:51]
	v_mfma_f32_16x16x32_bf16 v[36:39], v[164:167], v[188:191], v[36:39]
	v_mfma_f32_16x16x32_bf16 v[32:35], v[172:175], v[188:191], v[32:35]
	v_mfma_f32_16x16x32_bf16 v[20:23], v[164:167], v[206:209], v[20:23]
	v_mfma_f32_16x16x32_bf16 v[16:19], v[172:175], v[206:209], v[16:19]
	v_mfma_f32_16x16x32_bf16 v[4:7], v[164:167], v[214:217], v[4:7]
	v_mfma_f32_16x16x32_bf16 v[0:3], v[172:175], v[214:217], v[0:3]
	s_setprio 1
	s_barrier
	s_add_i32 s22, s22, 2
	s_add_u32 s2, s2, 0x100
	s_addc_u32 s3, s3, 0
	s_add_u32 s20, s20, 0x100
	s_addc_u32 s21, s21, 0
	s_cmp_gt_u32 s22, 29
	s_cbranch_scc0 .LBB0_347
	s_setprio 0
	s_and_b64 vcc, exec, s[8:9]
	s_cbranch_vccz .LBB0_350
	s_barrier
